# out-proj/down-proj: old residual rows loaded with lanes relabelled (64 contiguous bytes per lane quad) and restored with ds_bpermute behind the wait; on top of previous changes
# baseline (speedup 1.0000x reference)
;     __device__ __forceinline__ void init(f32x4 (&acc)[2][2][4][2], const Unit& u, int wr, int wc, int fr, int fq) const {
;         const int row0 = u.pm * BM + wr * 64 + fr; const int col0 = u.pn * BM + wc * 32 + 8 * fq;
;         const unsigned ob0 = ((unsigned)row0 * LDC + (unsigned)col0) * 2u; const char* bb = (const char*)xb;
; #pragma unroll
;         for (int ai = 0; ai < 2; ++ai)
; #pragma unroll
;             for (int m = 0; m < 4; ++m) { const unsigned o = ob0 + (unsigned)((ai * HALF + m * 16) * LDC * 2);
; #pragma unroll
;                 for (int bj = 0; bj < 2; ++bj) { const u32x4 w = *(const u32x4*)(bb + o + bj * HALF * 2);
;                     acc[ai][bj][m][0] = (f32x4){blo(w.x), bhi(w.x), blo(w.y), bhi(w.y)}; acc[ai][bj][m][1] = (f32x4){blo(w.z), bhi(w.z), blo(w.w), bhi(w.w)}; } }
;     }
; template <class Epi, class Sched, bool ALIGN_EPI = false, bool SP2 = false>
; __device__ __forceinline__ void gemm_phase(PG8_LAS unsigned char* lds, const Gemm g, const Sched& S, const Epi& E, const int wid_in) {
;     ...
;     for (int i = 0; i < 2; ++i) { int R, C; stage_rc(tid * 16 + i * 8192, R, C); const int Rb = Epi::PERM ? ((R & ~31) + perm32(R & 31)) : R;
;         voffA[i] = (unsigned)(R * g.lda + C) * 2u; voffB[i] = (unsigned)(Rb * K + C) * 2u; }
;     const size_t kstep = (size_t)(BK * 2);
;     const size_t hstep = (size_t)HALF * K * 2, tstep = 2 * hstep;
;     const size_t hstepA = (size_t)HALF * g.lda * 2, tstepA = 2 * hstepA;
;     const unsigned ldsw = (unsigned)wid * 1024u;
;     const int aoff = lds_byte(wr * 64 + fr, fq * 8), boff = lds_byte(wc * 32 + fr, fq * 8);
;     ...
;     Unit cur, nxt; int ui = 0;
;     if (!S.next(0, cur)) return;
;     f32x4 acc[2][2][4][2];
;     E.init(acc, cur, wr, wc, fr, fq);
;     bf16x8 At[4][2], B0[2][2], B1[2][2];
;     const char* cA = (const char*)g.A + (size_t)cur.pm * tstepA; const char* cB = (const char*)g.Bt + (size_t)cur.pn * tstep;
;     S.a_ready(cur);
;     if constexpr (SP2) {
;         PG8_STAGE(PG8_SB(0, 0), cB, voffB); PG8_STAGE(PG8_SB(0, 1), cB + hstep, voffB); PG8_STAGE(PG8_SA(0, 0), cA, voffA); PG8_STAGE(PG8_SA(0, 1), cA + hstepA, voffA);
;         if (wr == 1) PG8_BAR;
;         PG8_WAIT_V(2); PG8_BAR;
;         PG8_STAGE(PG8_SB(1, 0), cB + kstep, voffB); PG8_STAGE(PG8_SA(1, 0), cA + kstep, voffA); PG8_STAGE(PG8_SB(1, 1), cB + hstep + kstep, voffB);
;         PG8_WAIT_V(6); PG8_BAR;
.LBB0_360:
	s_or_b64 exec, exec, s[0:1]
	v_readlane_b32 s12, v252, 56
	v_readlane_b32 s0, v252, 13
	v_readlane_b32 s13, v252, 57
	v_readlane_b32 s1, v252, 14
	v_readlane_b32 s2, v252, 15
	v_readlane_b32 s3, v252, 16
	v_cndmask_b32_e64 v1, 0, 1, s[12:13]
	s_mov_b64 s[8:9], s[2:3]
	s_mov_b64 s[6:7], s[2:3]
	s_mov_b64 s[0:1], s[2:3]
	v_readlane_b32 s10, v252, 37
	v_cmp_ne_u32_e64 s[4:5], 1, v1
	s_andn2_b64 vcc, exec, s[12:13]
	s_waitcnt lgkmcnt(0)
	s_barrier
	v_mbcnt_lo_u32_b32 v139, -1, 0
	v_mbcnt_hi_u32_b32 v139, -1, v139
	s_cbranch_vccnz .LBB0_398
	s_add_u32 s30, s8, 0xf801000
	s_addc_u32 s31, s9, 0
	v_readlane_b32 s8, v251, 41
	v_readlane_b32 s9, v251, 42
	s_lshl_b64 s[8:9], s[8:9], 23
	s_add_u32 s6, s6, s8
	s_addc_u32 s7, s7, s9
	s_add_u32 s34, s6, 0x2800000
	s_addc_u32 s35, s7, 0
	s_add_u32 s12, s0, 0xb800000
	s_addc_u32 s13, s1, 0
	s_lshl_b32 s37, s10, 10
	v_lshlrev_b32_e32 v153, 4, v139
	v_add_u32_e32 v1, s37, v153
	v_add_u32_e32 v2, 0x2000, v1
	v_ashrrev_i32_e32 v3, 31, v2
	v_lshrrev_b32_e32 v3, 22, v3
	v_add_u32_e32 v3, v2, v3
	v_ashrrev_i32_e32 v145, 10, v3
	v_mul_i32_i24_e32 v3, 0x400, v145
	v_sub_u32_e32 v2, v2, v3
	v_lshrrev_b32_e32 v3, 4, v2
	v_bitop3_b32 v2, v3, v2, 32 bitop3:0x6c
	v_ashrrev_i32_e32 v3, 31, v2
	v_lshrrev_b32_e32 v3, 26, v3
	v_add_u32_e32 v3, v2, v3
	v_ashrrev_i32_e32 v150, 6, v3
	v_lshlrev_b32_e32 v4, 3, v145
	v_and_b32_e32 v3, 0xffc0, v3
	v_and_b32_e32 v4, -16, v4
	v_sub_u32_e32 v2, v2, v3
	v_add_u32_e32 v4, v150, v4
	v_lshrrev_b16_e32 v3, 7, v2
	v_and_b32_e32 v5, 3, v150
	s_mov_b32 s6, 0xfffe0
	v_lshrrev_b32_e32 v6, 2, v4
	v_lshlrev_b32_e32 v7, 1, v4
	v_and_b32_e32 v3, 1, v3
	v_and_or_b32 v5, v4, s6, v5
	v_and_b32_e32 v6, 4, v6
	v_and_b32_e32 v7, 24, v7
	v_add_u16_e32 v2, v2, v3
	v_or3_b32 v5, v5, v6, v7
	v_lshlrev_b32_e32 v6, 5, v145
	v_ashrrev_i16_sdwa v2, v195, sext(v2) dst_sel:DWORD dst_unused:UNUSED_PAD src0_sel:DWORD src1_sel:BYTE_0
	v_and_b32_e32 v151, 32, v6
	v_bfe_i32 v152, v2, 0, 16
	v_add_u32_e32 v2, v151, v152
	v_lshlrev_b32_e32 v3, 1, v2
	s_movk_i32 s7, 0x1400
	v_lshl_add_u32 v130, v5, 12, v3
	v_mul_lo_u32 v3, v4, s7
	v_add_lshl_u32 v132, v2, v3, 1
	v_ashrrev_i32_e32 v2, 31, v1
	v_lshrrev_b32_e32 v2, 22, v2
	v_add_u32_e32 v2, v1, v2
	v_ashrrev_i32_e32 v166, 10, v2
	v_mul_i32_i24_e32 v2, 0x400, v166
	v_sub_u32_e32 v1, v1, v2
	v_lshrrev_b32_e32 v2, 4, v1
	v_bitop3_b32 v1, v2, v1, 32 bitop3:0x6c
	v_ashrrev_i32_e32 v2, 31, v1
	v_lshrrev_b32_e32 v2, 26, v2
	v_add_u32_e32 v2, v1, v2
	v_lshlrev_b32_e32 v3, 3, v166
	v_ashrrev_i32_e32 v167, 6, v2
	v_and_b32_e32 v3, -16, v3
	v_add_u32_e32 v3, v167, v3
	v_and_b32_e32 v4, 3, v167
	v_lshrrev_b32_e32 v5, 2, v3
	v_lshlrev_b32_e32 v6, 1, v3
	v_and_b32_e32 v2, 0xc0, v2
	v_and_or_b32 v4, v3, s6, v4
	v_and_b32_e32 v5, 4, v5
	v_and_b32_e32 v6, 24, v6
	v_sub_u32_e32 v1, v1, v2
	v_or3_b32 v4, v4, v5, v6
	v_lshlrev_b32_e32 v5, 5, v166
	v_ashrrev_i16_sdwa v1, v195, sext(v1) dst_sel:DWORD dst_unused:UNUSED_PAD src0_sel:DWORD src1_sel:BYTE_0
	v_and_b32_e32 v168, 32, v5
	v_bfe_i32 v169, v1, 0, 16
	s_ashr_i32 s1, s10, 2
	v_add_u32_e32 v1, v168, v169
	s_lshl_b32 s0, s1, 6
	v_lshlrev_b32_e32 v2, 1, v1
	v_readlane_b32 s6, v251, 3
	v_and_b32_e32 v144, 15, v139
	v_lshl_add_u32 v134, v4, 12, v2
	v_mul_lo_u32 v2, v3, s7
	s_add_i32 s6, s6, s0
	s_and_b32 s36, s10, 3
	v_add_lshl_u32 v136, v1, v2, 1
	v_or_b32_e32 v1, s6, v144
	v_and_b32_e32 v138, -16, v139
	v_lshlrev_b32_e32 v1, 12, v1
	v_lshl_add_u32 v170, s36, 6, v138
	v_readlane_b32 s6, v251, 5
	v_mov_b32_e32 v135, v0
	v_mov_b32_e32 v131, v0
	v_add3_u32 v1, s6, v170, v1
	v_mbcnt_lo_u32_b32 v66, -1, 0
	v_mbcnt_hi_u32_b32 v66, -1, v66
	v_lshrrev_b32_e32 v67, 2, v66
	v_and_b32_e32 v68, 15, v66
	v_sub_u32_e32 v67, v67, v68
	v_lshlrev_b32_e32 v67, 12, v67
	v_and_b32_e32 v68, 3, v66
	v_lshrrev_b32_e32 v66, 4, v66
	v_sub_u32_e32 v68, v68, v66
	v_lshl_add_u32 v67, v68, 4, v67
	v_add_u32_e32 v1, v1, v67
	v_add_u32_e32 v2, 0x10000, v1
	global_load_dwordx4 v[62:65], v1, s[12:13]
	global_load_dwordx4 v[58:61], v1, s[12:13] offset:256
	global_load_dwordx4 v[54:57], v2, s[12:13]
	global_load_dwordx4 v[50:53], v2, s[12:13] offset:256
	v_add_u32_e32 v2, 0x20000, v1
	global_load_dwordx4 v[46:49], v2, s[12:13]
	global_load_dwordx4 v[42:45], v2, s[12:13] offset:256
	v_add_u32_e32 v2, 0x30000, v1
	v_readlane_b32 s6, v251, 6
	global_load_dwordx4 v[38:41], v2, s[12:13]
	global_load_dwordx4 v[34:37], v2, s[12:13] offset:256
	v_add_u32_e32 v2, 0x80000, v1
	v_readlane_b32 s7, v251, 7
	s_add_u32 s28, s34, s6
	global_load_dwordx4 v[14:17], v2, s[12:13]
	global_load_dwordx4 v[10:13], v2, s[12:13] offset:256
	v_add_u32_e32 v2, 0x90000, v1
	s_addc_u32 s29, s35, s7
	s_add_i32 s38, s37, 0
	global_load_dwordx4 v[6:9], v2, s[12:13]
	global_load_dwordx4 v[26:29], v2, s[12:13] offset:256
	v_add_u32_e32 v2, 0xa0000, v1
	v_add_u32_e32 v1, 0xb0000, v1
	s_add_i32 m0, s38, 0x10000
	global_load_dwordx4 v[22:25], v2, s[12:13]
	global_load_dwordx4 v[18:21], v2, s[12:13] offset:256
	s_nop 0
	global_load_dwordx4 v[2:5], v1, s[12:13]
	global_load_dwordx4 v[30:33], v1, s[12:13] offset:256
	v_mov_b32_e32 v137, v0
	global_load_lds_dwordx4 v134, s[28:29]
	s_add_i32 m0, s38, 0x12000
	s_add_u32 s6, s28, 0x80000
	global_load_lds_dwordx4 v130, s[28:29]
	s_addc_u32 s7, s29, 0
	s_add_i32 m0, s38, 0x14000
	v_mov_b32_e32 v133, v0
	global_load_lds_dwordx4 v134, s[6:7]
	s_add_i32 m0, s38, 0x16000
	v_lshl_add_u64 v[148:149], s[28:29], 0, v[134:135]
	global_load_lds_dwordx4 v130, s[6:7]
	v_readlane_b32 s6, v251, 31
	s_mov_b32 s8, s6
	s_mul_i32 s6, s6, 0x280000
	s_add_u32 s26, s30, s6
	s_mul_hi_i32 s6, s8, 0x280000
	s_addc_u32 s27, s31, s6
	s_add_i32 s39, s38, 0x2000
	v_readlane_b32 s7, v251, 32
	s_mov_b32 m0, s38
	s_add_u32 s6, s26, 0x140000
	global_load_lds_dwordx4 v136, s[26:27]
	s_mov_b32 m0, s39
	s_addc_u32 s7, s27, 0
	s_add_i32 s40, s38, 0x4000
	global_load_lds_dwordx4 v132, s[26:27]
	s_mov_b32 m0, s40
	s_add_i32 s41, s38, 0x6000
	global_load_lds_dwordx4 v136, s[6:7]
	s_mov_b32 m0, s41
	s_cmp_eq_u32 s1, 1
	global_load_lds_dwordx4 v132, s[6:7]
	v_lshl_add_u64 v[146:147], s[28:29], 0, v[130:131]
	v_lshl_add_u64 v[140:141], s[26:27], 0, v[136:137]
	s_cselect_b64 s[14:15], -1, 0
	s_cmp_lg_u32 s1, 1
	v_lshl_add_u64 v[142:143], s[26:27], 0, v[132:133]
	s_cbranch_scc1 .LBB0_363
	s_barrier
; #define PG8_STAGE(bufoff, gbase, voff) do { _Pragma("unroll") for (int _i = 0; _i < 2; ++_i) \
;         __builtin_amdgcn_global_load_lds((const unsigned*)((const char*)(gbase) + (voff)[_i]), (PG8_LAS unsigned*)(lds + (bufoff) + ldsw + _i * 8192), 16, 0, 0); } while (0)
; #define PG8_WAIT_V(n) asm volatile("s_waitcnt vmcnt(" #n ")" ::: "memory")
; #define PG8_BAR __builtin_amdgcn_s_barrier()
;     __device__ __forceinline__ void init(f32x4 (&acc)[2][2][4][2], const Unit& u, int wr, int wc, int fr, int fq) const {
;     ...
;                 for (int bj = 0; bj < 2; ++bj) { const u32x4 w = *(const u32x4*)(bb + o + bj * HALF * 2);
;                     acc[ai][bj][m][0] = (f32x4){blo(w.x), bhi(w.x), blo(w.y), bhi(w.y)}; acc[ai][bj][m][1] = (f32x4){blo(w.z), bhi(w.z), blo(w.w), bhi(w.w)}; } }
; template <class Epi, class Sched, bool ALIGN_EPI = false, bool SP2 = false>
; __device__ __forceinline__ void gemm_phase(PG8_LAS unsigned char* lds, const Gemm g, const Sched& S, const Epi& E, const int wid_in) {
;     ...
;         PG8_WAIT_V(2); PG8_BAR;
;         PG8_STAGE(PG8_SB(1, 0), cB + kstep, voffB); PG8_STAGE(PG8_SA(1, 0), cA + kstep, voffA); PG8_STAGE(PG8_SB(1, 1), cB + hstep + kstep, voffB);
;         PG8_WAIT_V(6); PG8_BAR;
.LBB0_363:
	s_add_u32 s42, s2, 0x1fe00000
	s_waitcnt vmcnt(0)
	ds_bpermute_b32 v2, v254, v2
	ds_bpermute_b32 v3, v254, v3
	ds_bpermute_b32 v4, v254, v4
	ds_bpermute_b32 v5, v254, v5
	ds_bpermute_b32 v6, v254, v6
	ds_bpermute_b32 v7, v254, v7
	ds_bpermute_b32 v8, v254, v8
	ds_bpermute_b32 v9, v254, v9
	ds_bpermute_b32 v10, v254, v10
	ds_bpermute_b32 v11, v254, v11
	ds_bpermute_b32 v12, v254, v12
	ds_bpermute_b32 v13, v254, v13
	ds_bpermute_b32 v14, v254, v14
	ds_bpermute_b32 v15, v254, v15
	ds_bpermute_b32 v16, v254, v16
	ds_bpermute_b32 v17, v254, v17
	ds_bpermute_b32 v18, v254, v18
	ds_bpermute_b32 v19, v254, v19
	ds_bpermute_b32 v20, v254, v20
	ds_bpermute_b32 v21, v254, v21
	ds_bpermute_b32 v22, v254, v22
	ds_bpermute_b32 v23, v254, v23
	ds_bpermute_b32 v24, v254, v24
	ds_bpermute_b32 v25, v254, v25
	ds_bpermute_b32 v26, v254, v26
	ds_bpermute_b32 v27, v254, v27
	ds_bpermute_b32 v28, v254, v28
	ds_bpermute_b32 v29, v254, v29
	ds_bpermute_b32 v30, v254, v30
	ds_bpermute_b32 v31, v254, v31
	ds_bpermute_b32 v32, v254, v32
	ds_bpermute_b32 v33, v254, v33
	ds_bpermute_b32 v34, v254, v34
	ds_bpermute_b32 v35, v254, v35
	ds_bpermute_b32 v36, v254, v36
	ds_bpermute_b32 v37, v254, v37
	ds_bpermute_b32 v38, v254, v38
	ds_bpermute_b32 v39, v254, v39
	ds_bpermute_b32 v40, v254, v40
	ds_bpermute_b32 v41, v254, v41
	ds_bpermute_b32 v42, v254, v42
	ds_bpermute_b32 v43, v254, v43
	ds_bpermute_b32 v44, v254, v44
	ds_bpermute_b32 v45, v254, v45
	ds_bpermute_b32 v46, v254, v46
	ds_bpermute_b32 v47, v254, v47
	ds_bpermute_b32 v48, v254, v48
	ds_bpermute_b32 v49, v254, v49
	ds_bpermute_b32 v50, v254, v50
	ds_bpermute_b32 v51, v254, v51
	ds_bpermute_b32 v52, v254, v52
	ds_bpermute_b32 v53, v254, v53
	ds_bpermute_b32 v54, v254, v54
	ds_bpermute_b32 v55, v254, v55
	ds_bpermute_b32 v56, v254, v56
	ds_bpermute_b32 v57, v254, v57
	ds_bpermute_b32 v58, v254, v58
	ds_bpermute_b32 v59, v254, v59
	ds_bpermute_b32 v60, v254, v60
	ds_bpermute_b32 v61, v254, v61
	ds_bpermute_b32 v62, v254, v62
	ds_bpermute_b32 v63, v254, v63
	ds_bpermute_b32 v64, v254, v64
	ds_bpermute_b32 v65, v254, v65
	s_waitcnt lgkmcnt(0)
	v_lshlrev_b32_e32 v86, 16, v42
	v_and_b32_e32 v87, 0xffff0000, v42
	v_lshlrev_b32_e32 v88, 16, v43
	v_and_b32_e32 v89, 0xffff0000, v43
	s_addc_u32 s43, s3, 0
	s_add_i32 m0, s38, 0x18000
	v_lshl_add_u64 v[42:43], v[148:149], 0, s[98:99]
	s_waitcnt vmcnt(2)
	s_barrier
	global_load_lds_dwordx4 v[42:43], off
	v_lshl_add_u64 v[42:43], v[146:147], 0, s[98:99]
	s_add_i32 m0, s38, 0x1a000
	s_add_i32 s44, s38, 0x8000
	s_add_i32 s45, s38, 0xa000
	global_load_lds_dwordx4 v[42:43], off
	v_lshl_add_u64 v[42:43], v[140:141], 0, s[98:99]
	s_mov_b32 m0, s44
	s_add_u32 s2, s28, 0x80080
	global_load_lds_dwordx4 v[42:43], off
	v_lshl_add_u64 v[42:43], v[142:143], 0, s[98:99]
	s_mov_b32 m0, s45
	s_addc_u32 s3, s29, 0
	global_load_lds_dwordx4 v[42:43], off
	s_add_i32 m0, s38, 0x1c000
	v_lshl_add_u64 v[42:43], s[2:3], 0, v[134:135]
	global_load_lds_dwordx4 v[42:43], off
	v_lshl_add_u64 v[42:43], s[2:3], 0, v[130:131]
	s_add_i32 m0, s38, 0x1e000
	v_or_b32_e32 v146, s0, v144
	global_load_lds_dwordx4 v[42:43], off
	v_ashrrev_i32_e32 v1, 4, v139
	v_lshlrev_b32_e32 v140, 6, v146
	v_and_b32_e32 v139, 48, v139
	s_movk_i32 s2, 0x3c0
	v_and_b32_e32 v141, 0xfffffc00, v153
	v_lshlrev_b32_e32 v143, 2, v146
	v_and_or_b32 v140, v140, s2, v139
	v_lshl_add_u32 v142, s1, 13, v141
	v_and_b32_e32 v143, 32, v143
	v_bitop3_b32 v153, v140, v142, v143 bitop3:0xde
	v_lshl_add_u32 v140, s36, 12, v141
	v_lshlrev_b32_e32 v141, 2, v144
	v_lshl_or_b32 v139, v144, 6, v139
	v_and_b32_e32 v141, 32, v141
	s_movk_i32 s9, 0x1400
	v_bitop3_b32 v147, v139, v140, v141 bitop3:0xde
	s_cmp_lt_u32 s10, 4
	v_lshrrev_b32_e32 v141, 1, v166
	v_mul_lo_u32 v140, v167, s9
	s_mov_b32 s8, 0x14000
	v_lshrrev_b32_e32 v143, 1, v145
	v_mul_lo_u32 v142, v150, s9
	s_cselect_b64 s[16:17], -1, 0
	s_lshl_b32 s1, s36, 7
	v_mad_u64_u32 v[140:141], s[2:3], v141, s8, v[140:141]
	v_mad_u64_u32 v[142:143], s[2:3], v143, s8, v[142:143]
	s_waitcnt vmcnt(6)
	v_lshl_add_u32 v148, v1, 5, s1
	s_ashr_i32 s1, s0, 31
	v_or_b32_e32 v140, v140, v168
	v_or_b32_e32 v142, v142, v151
	v_add_lshl_u32 v140, v140, v169, 1
	v_mov_b32_e32 v141, v0
	s_mov_b64 s[10:11], 0x140080
	v_add_lshl_u32 v142, v142, v152, 1
	v_mov_b32_e32 v143, v0
	s_lshl_b64 s[18:19], s[0:1], 2
	v_readlane_b32 s0, v251, 31
	v_lshlrev_b32_e32 v118, 16, v62
	v_and_b32_e32 v119, 0xffff0000, v62
	v_lshlrev_b32_e32 v120, 16, v63
	v_and_b32_e32 v121, 0xffff0000, v63
	v_lshlrev_b32_e32 v114, 16, v64
	v_and_b32_e32 v115, 0xffff0000, v64
	v_lshlrev_b32_e32 v116, 16, v65
	v_and_b32_e32 v117, 0xffff0000, v65
	v_lshlrev_b32_e32 v122, 16, v58
	v_and_b32_e32 v123, 0xffff0000, v58
	v_lshlrev_b32_e32 v124, 16, v59
	v_and_b32_e32 v125, 0xffff0000, v59
	v_lshlrev_b32_e32 v126, 16, v60
	v_and_b32_e32 v127, 0xffff0000, v60
	v_lshlrev_b32_e32 v128, 16, v61
	v_and_b32_e32 v129, 0xffff0000, v61
	v_lshlrev_b32_e32 v98, 16, v54
	v_and_b32_e32 v99, 0xffff0000, v54
	v_lshlrev_b32_e32 v100, 16, v55
	v_and_b32_e32 v101, 0xffff0000, v55
	v_lshlrev_b32_e32 v106, 16, v56
	v_and_b32_e32 v107, 0xffff0000, v56
	v_lshlrev_b32_e32 v108, 16, v57
	v_and_b32_e32 v109, 0xffff0000, v57
	v_lshlrev_b32_e32 v102, 16, v50
	v_and_b32_e32 v103, 0xffff0000, v50
	v_lshlrev_b32_e32 v104, 16, v51
	v_and_b32_e32 v105, 0xffff0000, v51
	v_lshlrev_b32_e32 v110, 16, v52
	v_and_b32_e32 v111, 0xffff0000, v52
	v_lshlrev_b32_e32 v112, 16, v53
	v_and_b32_e32 v113, 0xffff0000, v53
	v_lshlrev_b32_e32 v82, 16, v46
	v_and_b32_e32 v83, 0xffff0000, v46
	v_lshlrev_b32_e32 v84, 16, v47
	v_and_b32_e32 v85, 0xffff0000, v47
	v_lshlrev_b32_e32 v90, 16, v48
;     __device__ __forceinline__ void init(f32x4 (&acc)[2][2][4][2], const Unit& u, int wr, int wc, int fr, int fq) const {
;     ...
;                 for (int bj = 0; bj < 2; ++bj) { const u32x4 w = *(const u32x4*)(bb + o + bj * HALF * 2);
;                     acc[ai][bj][m][0] = (f32x4){blo(w.x), bhi(w.x), blo(w.y), bhi(w.y)}; acc[ai][bj][m][1] = (f32x4){blo(w.z), bhi(w.z), blo(w.w), bhi(w.w)}; } }
; template <class Epi, class Sched, bool ALIGN_EPI = false, bool SP2 = false>
; __device__ __forceinline__ void gemm_phase(PG8_LAS unsigned char* lds, const Gemm g, const Sched& S, const Epi& E, const int wid_in) {
;     ...
;     const int aoff = lds_byte(wr * 64 + fr, fq * 8), boff = lds_byte(wc * 32 + fr, fq * 8);
	v_and_b32_e32 v91, 0xffff0000, v48
	v_lshlrev_b32_e32 v92, 16, v49
	v_and_b32_e32 v93, 0xffff0000, v49
	v_lshlrev_b32_e32 v94, 16, v44
	v_and_b32_e32 v95, 0xffff0000, v44
	v_lshlrev_b32_e32 v96, 16, v45
	v_and_b32_e32 v97, 0xffff0000, v45
	v_lshlrev_b32_e32 v74, 16, v38
	v_and_b32_e32 v75, 0xffff0000, v38
	v_lshlrev_b32_e32 v76, 16, v39
	v_and_b32_e32 v77, 0xffff0000, v39
	v_lshlrev_b32_e32 v66, 16, v40
	v_and_b32_e32 v67, 0xffff0000, v40
	v_lshlrev_b32_e32 v68, 16, v41
	v_and_b32_e32 v69, 0xffff0000, v41
	v_lshlrev_b32_e32 v70, 16, v34
	v_and_b32_e32 v71, 0xffff0000, v34
	v_lshlrev_b32_e32 v72, 16, v35
	v_and_b32_e32 v73, 0xffff0000, v35
	v_lshlrev_b32_e32 v78, 16, v36
	v_and_b32_e32 v79, 0xffff0000, v36
	v_lshlrev_b32_e32 v80, 16, v37
	v_and_b32_e32 v81, 0xffff0000, v37
	v_lshlrev_b32_e32 v34, 16, v14
	v_and_b32_e32 v35, 0xffff0000, v14
	v_lshlrev_b32_e32 v36, 16, v15
	v_and_b32_e32 v37, 0xffff0000, v15
	v_lshlrev_b32_e32 v46, 16, v16
	v_and_b32_e32 v47, 0xffff0000, v16
	v_lshlrev_b32_e32 v48, 16, v17
	v_and_b32_e32 v49, 0xffff0000, v17
	v_lshlrev_b32_e32 v38, 16, v10
	v_and_b32_e32 v39, 0xffff0000, v10
	v_lshlrev_b32_e32 v40, 16, v11
	v_and_b32_e32 v41, 0xffff0000, v11
	v_lshlrev_b32_e32 v54, 16, v12
	v_and_b32_e32 v55, 0xffff0000, v12
	v_lshlrev_b32_e32 v56, 16, v13
	v_and_b32_e32 v57, 0xffff0000, v13
	v_lshlrev_b32_e32 v10, 16, v6
	v_and_b32_e32 v11, 0xffff0000, v6
	v_lshlrev_b32_e32 v12, 16, v7
	v_and_b32_e32 v13, 0xffff0000, v7
	v_lshlrev_b32_e32 v6, 16, v8
	v_and_b32_e32 v7, 0xffff0000, v8
	v_lshlrev_b32_e32 v8, 16, v9
	v_and_b32_e32 v9, 0xffff0000, v9
	v_lshlrev_b32_e32 v14, 16, v26
	v_and_b32_e32 v15, 0xffff0000, v26
	v_lshlrev_b32_e32 v16, 16, v27
	v_and_b32_e32 v17, 0xffff0000, v27
	v_lshlrev_b32_e32 v26, 16, v28
	v_and_b32_e32 v27, 0xffff0000, v28
	v_lshlrev_b32_e32 v28, 16, v29
	v_and_b32_e32 v29, 0xffff0000, v29
	v_lshlrev_b32_e32 v42, 16, v22
	v_and_b32_e32 v43, 0xffff0000, v22
	v_lshlrev_b32_e32 v44, 16, v23
	v_and_b32_e32 v45, 0xffff0000, v23
	v_lshlrev_b32_e32 v58, 16, v24
	v_and_b32_e32 v59, 0xffff0000, v24
	v_lshlrev_b32_e32 v60, 16, v25
	v_and_b32_e32 v61, 0xffff0000, v25
	v_lshlrev_b32_e32 v50, 16, v18
	v_and_b32_e32 v51, 0xffff0000, v18
	v_lshlrev_b32_e32 v52, 16, v19
	v_and_b32_e32 v53, 0xffff0000, v19
	v_lshlrev_b32_e32 v62, 16, v20
	v_and_b32_e32 v63, 0xffff0000, v20
	v_lshlrev_b32_e32 v64, 16, v21
	v_and_b32_e32 v65, 0xffff0000, v21
	v_lshlrev_b32_e32 v22, 16, v2
	v_and_b32_e32 v23, 0xffff0000, v2
	v_lshlrev_b32_e32 v24, 16, v3
	v_and_b32_e32 v25, 0xffff0000, v3
	v_lshlrev_b32_e32 v2, 16, v4
	v_and_b32_e32 v3, 0xffff0000, v4
	v_lshlrev_b32_e32 v4, 16, v5
	v_and_b32_e32 v5, 0xffff0000, v5
	v_lshlrev_b32_e32 v18, 16, v30
	v_and_b32_e32 v19, 0xffff0000, v30
	v_lshlrev_b32_e32 v20, 16, v31
	v_and_b32_e32 v21, 0xffff0000, v31
	v_lshlrev_b32_e32 v30, 16, v32
	v_and_b32_e32 v31, 0xffff0000, v32
	v_lshlrev_b32_e32 v32, 16, v33
	v_and_b32_e32 v33, 0xffff0000, v33
	v_cmp_eq_u32_e64 s[6:7], 2, v1
	v_ashrrev_i32_e32 v139, 31, v138
	v_lshl_add_u32 v149, v146, 12, v170
	v_lshl_add_u64 v[140:141], v[140:141], 0, s[10:11]
	v_lshl_add_u64 v[142:143], v[142:143], 0, s[10:11]
	s_mov_b32 s46, 0
	v_add_u32_e32 v150, 0, v153
	v_lshlrev_b32_e32 v144, 2, v144
	v_readlane_b32 s33, v251, 4
	s_mov_b32 s48, s0
	s_barrier
	v_readlane_b32 s1, v251, 32
	s_branch .LBB0_366
;     __device__ __forceinline__ void init(f32x4 (&acc)[2][2][4][2], const Unit& u, int wr, int wc, int fr, int fq) const {
;     ...
;                 for (int bj = 0; bj < 2; ++bj) { const u32x4 w = *(const u32x4*)(bb + o + bj * HALF * 2);
;                     acc[ai][bj][m][0] = (f32x4){blo(w.x), bhi(w.x), blo(w.y), bhi(w.y)}; acc[ai][bj][m][1] = (f32x4){blo(w.z), bhi(w.z), blo(w.w), bhi(w.w)}; } }
; template <class Epi, class Sched, bool ALIGN_EPI = false, bool SP2 = false>
; __device__ __forceinline__ void gemm_phase(PG8_LAS unsigned char* lds, const Gemm g, const Sched& S, const Epi& E, const int wid_in) {
;     ...
;         E.init(acc, nxt, wr, wc, fr, fq);
.LBB0_364:
	s_waitcnt vmcnt(0)
	ds_bpermute_b32 v2, v254, v2
	ds_bpermute_b32 v3, v254, v3
	ds_bpermute_b32 v4, v254, v4
	ds_bpermute_b32 v5, v254, v5
	ds_bpermute_b32 v6, v254, v6
	ds_bpermute_b32 v7, v254, v7
	ds_bpermute_b32 v8, v254, v8
	ds_bpermute_b32 v9, v254, v9
	ds_bpermute_b32 v10, v254, v10
	ds_bpermute_b32 v11, v254, v11
	ds_bpermute_b32 v12, v254, v12
	ds_bpermute_b32 v13, v254, v13
	ds_bpermute_b32 v14, v254, v14
	ds_bpermute_b32 v15, v254, v15
	ds_bpermute_b32 v16, v254, v16
	ds_bpermute_b32 v17, v254, v17
	ds_bpermute_b32 v18, v254, v18
	ds_bpermute_b32 v19, v254, v19
	ds_bpermute_b32 v20, v254, v20
	ds_bpermute_b32 v21, v254, v21
	ds_bpermute_b32 v22, v254, v22
	ds_bpermute_b32 v23, v254, v23
	ds_bpermute_b32 v24, v254, v24
	ds_bpermute_b32 v25, v254, v25
	ds_bpermute_b32 v26, v254, v26
	ds_bpermute_b32 v27, v254, v27
	ds_bpermute_b32 v28, v254, v28
	ds_bpermute_b32 v29, v254, v29
	ds_bpermute_b32 v30, v254, v30
	ds_bpermute_b32 v31, v254, v31
	ds_bpermute_b32 v32, v254, v32
	ds_bpermute_b32 v33, v254, v33
	ds_bpermute_b32 v34, v254, v34
	ds_bpermute_b32 v35, v254, v35
	ds_bpermute_b32 v36, v254, v36
	ds_bpermute_b32 v37, v254, v37
	ds_bpermute_b32 v38, v254, v38
	ds_bpermute_b32 v39, v254, v39
	ds_bpermute_b32 v40, v254, v40
	ds_bpermute_b32 v41, v254, v41
	ds_bpermute_b32 v42, v254, v42
	ds_bpermute_b32 v43, v254, v43
	ds_bpermute_b32 v44, v254, v44
	ds_bpermute_b32 v45, v254, v45
	ds_bpermute_b32 v46, v254, v46
	ds_bpermute_b32 v47, v254, v47
	ds_bpermute_b32 v48, v254, v48
	ds_bpermute_b32 v49, v254, v49
	ds_bpermute_b32 v50, v254, v50
	ds_bpermute_b32 v51, v254, v51
	ds_bpermute_b32 v52, v254, v52
	ds_bpermute_b32 v53, v254, v53
	ds_bpermute_b32 v54, v254, v54
	ds_bpermute_b32 v55, v254, v55
	ds_bpermute_b32 v56, v254, v56
	ds_bpermute_b32 v57, v254, v57
	ds_bpermute_b32 v58, v254, v58
	ds_bpermute_b32 v59, v254, v59
	ds_bpermute_b32 v60, v254, v60
	ds_bpermute_b32 v61, v254, v61
	ds_bpermute_b32 v62, v254, v62
	ds_bpermute_b32 v63, v254, v63
	ds_bpermute_b32 v64, v254, v64
	ds_bpermute_b32 v65, v254, v65
	s_waitcnt lgkmcnt(0)
	v_lshlrev_b32_e32 v118, 16, v62
	v_and_b32_e32 v119, 0xffff0000, v62
	v_lshlrev_b32_e32 v120, 16, v63
	v_and_b32_e32 v121, 0xffff0000, v63
	v_lshlrev_b32_e32 v114, 16, v64
	v_and_b32_e32 v115, 0xffff0000, v64
	v_lshlrev_b32_e32 v116, 16, v65
	v_and_b32_e32 v117, 0xffff0000, v65
	v_lshlrev_b32_e32 v122, 16, v58
	v_and_b32_e32 v123, 0xffff0000, v58
	v_lshlrev_b32_e32 v124, 16, v59
	v_and_b32_e32 v125, 0xffff0000, v59
	v_lshlrev_b32_e32 v126, 16, v60
	v_and_b32_e32 v127, 0xffff0000, v60
	v_lshlrev_b32_e32 v128, 16, v61
	v_and_b32_e32 v129, 0xffff0000, v61
	v_lshlrev_b32_e32 v98, 16, v54
	v_and_b32_e32 v99, 0xffff0000, v54
	v_lshlrev_b32_e32 v100, 16, v55
	v_and_b32_e32 v101, 0xffff0000, v55
	v_lshlrev_b32_e32 v106, 16, v56
	v_and_b32_e32 v107, 0xffff0000, v56
	v_lshlrev_b32_e32 v108, 16, v57
	v_and_b32_e32 v109, 0xffff0000, v57
	v_lshlrev_b32_e32 v102, 16, v50
	v_and_b32_e32 v103, 0xffff0000, v50
	v_lshlrev_b32_e32 v104, 16, v51
	v_and_b32_e32 v105, 0xffff0000, v51
	v_lshlrev_b32_e32 v110, 16, v52
	v_and_b32_e32 v111, 0xffff0000, v52
	v_lshlrev_b32_e32 v112, 16, v53
	v_and_b32_e32 v113, 0xffff0000, v53
	v_lshlrev_b32_e32 v82, 16, v46
	v_and_b32_e32 v83, 0xffff0000, v46
	v_lshlrev_b32_e32 v84, 16, v47
	v_and_b32_e32 v85, 0xffff0000, v47
	v_lshlrev_b32_e32 v90, 16, v48
	v_and_b32_e32 v91, 0xffff0000, v48
	v_lshlrev_b32_e32 v92, 16, v49
	v_and_b32_e32 v93, 0xffff0000, v49
	v_lshlrev_b32_e32 v86, 16, v42
	v_and_b32_e32 v87, 0xffff0000, v42
	v_lshlrev_b32_e32 v88, 16, v43
	v_and_b32_e32 v89, 0xffff0000, v43
	v_lshlrev_b32_e32 v94, 16, v44
	v_and_b32_e32 v95, 0xffff0000, v44
	v_lshlrev_b32_e32 v96, 16, v45
	v_and_b32_e32 v97, 0xffff0000, v45
	v_lshlrev_b32_e32 v74, 16, v38
	v_and_b32_e32 v75, 0xffff0000, v38
	v_lshlrev_b32_e32 v76, 16, v39
	v_and_b32_e32 v77, 0xffff0000, v39
	v_lshlrev_b32_e32 v66, 16, v40
	v_and_b32_e32 v67, 0xffff0000, v40
	v_lshlrev_b32_e32 v68, 16, v41
	v_and_b32_e32 v69, 0xffff0000, v41
	v_lshlrev_b32_e32 v70, 16, v34
	v_and_b32_e32 v71, 0xffff0000, v34
	v_lshlrev_b32_e32 v72, 16, v35
	v_and_b32_e32 v73, 0xffff0000, v35
	v_lshlrev_b32_e32 v78, 16, v36
	v_and_b32_e32 v79, 0xffff0000, v36
	v_lshlrev_b32_e32 v80, 16, v37
	v_and_b32_e32 v81, 0xffff0000, v37
	v_lshlrev_b32_e32 v34, 16, v14
	v_and_b32_e32 v35, 0xffff0000, v14
	v_lshlrev_b32_e32 v36, 16, v15
	v_and_b32_e32 v37, 0xffff0000, v15
	v_lshlrev_b32_e32 v46, 16, v16
	v_and_b32_e32 v47, 0xffff0000, v16
	v_lshlrev_b32_e32 v48, 16, v17
	v_and_b32_e32 v49, 0xffff0000, v17
	v_lshlrev_b32_e32 v38, 16, v10
	v_and_b32_e32 v39, 0xffff0000, v10
	v_lshlrev_b32_e32 v40, 16, v11
	v_and_b32_e32 v41, 0xffff0000, v11
	v_lshlrev_b32_e32 v54, 16, v12
	v_and_b32_e32 v55, 0xffff0000, v12
	v_lshlrev_b32_e32 v56, 16, v13
	v_and_b32_e32 v57, 0xffff0000, v13
	v_lshlrev_b32_e32 v10, 16, v6
	v_and_b32_e32 v11, 0xffff0000, v6
	v_lshlrev_b32_e32 v12, 16, v7
	v_and_b32_e32 v13, 0xffff0000, v7
	v_lshlrev_b32_e32 v6, 16, v8
	v_and_b32_e32 v7, 0xffff0000, v8
	v_lshlrev_b32_e32 v8, 16, v9
	v_and_b32_e32 v9, 0xffff0000, v9
	v_lshlrev_b32_e32 v14, 16, v26
	v_and_b32_e32 v15, 0xffff0000, v26
	v_lshlrev_b32_e32 v16, 16, v27
	v_and_b32_e32 v17, 0xffff0000, v27
	v_lshlrev_b32_e32 v26, 16, v28
	v_and_b32_e32 v27, 0xffff0000, v28
	v_lshlrev_b32_e32 v28, 16, v29
	v_and_b32_e32 v29, 0xffff0000, v29
	v_lshlrev_b32_e32 v42, 16, v22
	v_and_b32_e32 v43, 0xffff0000, v22
	v_lshlrev_b32_e32 v44, 16, v23
	v_and_b32_e32 v45, 0xffff0000, v23
	v_lshlrev_b32_e32 v58, 16, v24
	v_and_b32_e32 v59, 0xffff0000, v24
	v_lshlrev_b32_e32 v60, 16, v25
	v_and_b32_e32 v61, 0xffff0000, v25
	v_lshlrev_b32_e32 v50, 16, v18
	v_and_b32_e32 v51, 0xffff0000, v18
	v_lshlrev_b32_e32 v52, 16, v19
	v_and_b32_e32 v53, 0xffff0000, v19
	v_lshlrev_b32_e32 v62, 16, v20
	v_and_b32_e32 v63, 0xffff0000, v20
	v_lshlrev_b32_e32 v64, 16, v21
	v_and_b32_e32 v65, 0xffff0000, v21
	v_lshlrev_b32_e32 v22, 16, v2
	v_and_b32_e32 v23, 0xffff0000, v2
	v_lshlrev_b32_e32 v24, 16, v3
	v_and_b32_e32 v25, 0xffff0000, v3
	v_lshlrev_b32_e32 v2, 16, v4
	v_and_b32_e32 v3, 0xffff0000, v4
	v_lshlrev_b32_e32 v4, 16, v5
	v_and_b32_e32 v5, 0xffff0000, v5
	v_lshlrev_b32_e32 v18, 16, v30
	v_and_b32_e32 v19, 0xffff0000, v30
	v_lshlrev_b32_e32 v20, 16, v31
	v_and_b32_e32 v21, 0xffff0000, v31
	v_lshlrev_b32_e32 v30, 16, v32
	v_and_b32_e32 v31, 0xffff0000, v32
	v_lshlrev_b32_e32 v32, 16, v33
	v_and_b32_e32 v33, 0xffff0000, v33
	s_mov_b64 s[0:1], 0

; #define PG8_BAR __builtin_amdgcn_s_barrier()
;     __device__ __forceinline__ void init(f32x4 (&acc)[2][2][4][2], const Unit& u, int wr, int wc, int fr, int fq) const {
;         const int row0 = u.pm * BM + wr * 64 + fr; const int col0 = u.pn * BM + wc * 32 + 8 * fq;
;         const unsigned ob0 = ((unsigned)row0 * LDC + (unsigned)col0) * 2u; const char* bb = (const char*)xb;
; #pragma unroll
;         for (int ai = 0; ai < 2; ++ai)
; #pragma unroll
;             for (int m = 0; m < 4; ++m) { const unsigned o = ob0 + (unsigned)((ai * HALF + m * 16) * LDC * 2);
; #pragma unroll
;                 for (int bj = 0; bj < 2; ++bj) { const u32x4 w = *(const u32x4*)(bb + o + bj * HALF * 2);
;                     acc[ai][bj][m][0] = (f32x4){blo(w.x), bhi(w.x), blo(w.y), bhi(w.y)}; acc[ai][bj][m][1] = (f32x4){blo(w.z), bhi(w.z), blo(w.w), bhi(w.w)}; } }
; template <class Epi, class Sched, bool ALIGN_EPI = false, bool SP2 = false>
; __device__ __forceinline__ void gemm_phase(PG8_LAS unsigned char* lds, const Gemm g, const Sched& S, const Epi& E, const int wid_in) {
;     ...
;         if constexpr (!Epi::AFTER_DRAIN) { E(acc, cur, wr, wc, fr, fq); S.done(cur); }
;         if (!has_next) break;
;         E.init(acc, nxt, wr, wc, fr, fq);
;         cur = nxt; cA = nA; cB = nB; ++ui;
;         if constexpr (ALIGN_EPI) { if (wr == 1) PG8_BAR; }
.LBB0_394:
	s_or_b64 exec, exec, s[2:3]
	s_and_b64 vcc, exec, s[8:9]
	s_mov_b64 s[0:1], -1
	global_store_dword v[66:67], v2, off offset:512
	s_cbranch_vccnz .LBB0_365
	s_lshl_b32 s0, s20, 9
	s_lshl_b32 s1, s47, 20
	s_add_i32 s1, s1, s0
	v_add_u32_e32 v2, s1, v149
	v_mbcnt_lo_u32_b32 v66, -1, 0
	v_mbcnt_hi_u32_b32 v66, -1, v66
	v_lshrrev_b32_e32 v67, 2, v66
	v_and_b32_e32 v68, 15, v66
	v_sub_u32_e32 v67, v67, v68
	v_lshlrev_b32_e32 v67, 12, v67
	v_and_b32_e32 v68, 3, v66
	v_lshrrev_b32_e32 v66, 4, v66
	v_sub_u32_e32 v68, v68, v66
	v_lshl_add_u32 v67, v68, 4, v67
	v_add_u32_e32 v2, v2, v67
	v_add_u32_e32 v3, 0x10000, v2
	global_load_dwordx4 v[62:65], v2, s[12:13]
	global_load_dwordx4 v[58:61], v2, s[12:13] offset:256
	global_load_dwordx4 v[54:57], v3, s[12:13]
	global_load_dwordx4 v[50:53], v3, s[12:13] offset:256
	v_add_u32_e32 v3, 0x20000, v2
	global_load_dwordx4 v[46:49], v3, s[12:13]
	global_load_dwordx4 v[42:45], v3, s[12:13] offset:256
	v_add_u32_e32 v3, 0x30000, v2
	global_load_dwordx4 v[38:41], v3, s[12:13]
	global_load_dwordx4 v[34:37], v3, s[12:13] offset:256
	v_add_u32_e32 v3, 0x80000, v2
	global_load_dwordx4 v[14:17], v3, s[12:13]
	global_load_dwordx4 v[10:13], v3, s[12:13] offset:256
	v_add_u32_e32 v3, 0x90000, v2
	global_load_dwordx4 v[6:9], v3, s[12:13]
	global_load_dwordx4 v[26:29], v3, s[12:13] offset:256
	v_add_u32_e32 v3, 0xa0000, v2
	v_add_u32_e32 v30, 0xb0000, v2
	global_load_dwordx4 v[22:25], v3, s[12:13]
	global_load_dwordx4 v[18:21], v3, s[12:13] offset:256
	s_waitcnt lgkmcnt(0)
	global_load_dwordx4 v[2:5], v30, s[12:13]
	s_nop 0
	global_load_dwordx4 v[30:33], v30, s[12:13] offset:256
	s_andn2_b64 vcc, exec, s[14:15]
	s_cbranch_vccnz .LBB0_364
	s_barrier
	s_branch .LBB0_364

;     __device__ __forceinline__ void init(f32x4 (&acc)[2][2][4][2], const Unit& u, int wr, int wc, int fr, int fq) const {
;         const int row0 = u.pm * BM + wr * 64 + fr; const int col0 = u.pn * BM + wc * 32 + 8 * fq;
;         const unsigned ob0 = ((unsigned)row0 * LDC + (unsigned)col0) * 2u; const char* bb = (const char*)xb;
; #pragma unroll
;         for (int ai = 0; ai < 2; ++ai)
; #pragma unroll
;             for (int m = 0; m < 4; ++m) { const unsigned o = ob0 + (unsigned)((ai * HALF + m * 16) * LDC * 2);
; #pragma unroll
;                 for (int bj = 0; bj < 2; ++bj) { const u32x4 w = *(const u32x4*)(bb + o + bj * HALF * 2);
;                     acc[ai][bj][m][0] = (f32x4){blo(w.x), bhi(w.x), blo(w.y), bhi(w.y)}; acc[ai][bj][m][1] = (f32x4){blo(w.z), bhi(w.z), blo(w.w), bhi(w.w)}; } }
;     }
; template <class Epi, class Sched, bool ALIGN_EPI = false, bool SP2 = false>
; __device__ __forceinline__ void gemm_phase(PG8_LAS unsigned char* lds, const Gemm g, const Sched& S, const Epi& E, const int wid_in) {
;     ...
;     for (int i = 0; i < 2; ++i) { int R, C; stage_rc(tid * 16 + i * 8192, R, C); const int Rb = Epi::PERM ? ((R & ~31) + perm32(R & 31)) : R;
;         voffA[i] = (unsigned)(R * g.lda + C) * 2u; voffB[i] = (unsigned)(Rb * K + C) * 2u; }
;     const size_t kstep = (size_t)(BK * 2);
;     const size_t hstep = (size_t)HALF * K * 2, tstep = 2 * hstep;
;     const size_t hstepA = (size_t)HALF * g.lda * 2, tstepA = 2 * hstepA;
;     const unsigned ldsw = (unsigned)wid * 1024u;
;     const int aoff = lds_byte(wr * 64 + fr, fq * 8), boff = lds_byte(wc * 32 + fr, fq * 8);
;     ...
;     Unit cur, nxt; int ui = 0;
;     if (!S.next(0, cur)) return;
;     f32x4 acc[2][2][4][2];
;     E.init(acc, cur, wr, wc, fr, fq);
;     bf16x8 At[4][2], B0[2][2], B1[2][2];
;     const char* cA = (const char*)g.A + (size_t)cur.pm * tstepA; const char* cB = (const char*)g.Bt + (size_t)cur.pn * tstep;
;     S.a_ready(cur);
;     if constexpr (SP2) {
;         PG8_STAGE(PG8_SB(0, 0), cB, voffB); PG8_STAGE(PG8_SB(0, 1), cB + hstep, voffB); PG8_STAGE(PG8_SA(0, 0), cA, voffA); PG8_STAGE(PG8_SA(0, 1), cA + hstepA, voffA);
;         if (wr == 1) PG8_BAR;
;         PG8_WAIT_V(2); PG8_BAR;
;         PG8_STAGE(PG8_SB(1, 0), cB + kstep, voffB); PG8_STAGE(PG8_SA(1, 0), cA + kstep, voffA); PG8_STAGE(PG8_SB(1, 1), cB + hstep + kstep, voffB);
;         PG8_WAIT_V(6); PG8_BAR;
.LBB0_532:
	s_or_b64 exec, exec, s[0:1]
	v_readlane_b32 s0, v252, 13
	v_readlane_b32 s1, v252, 14
	v_readlane_b32 s2, v252, 15
	v_readlane_b32 s3, v252, 16
	s_mov_b64 s[6:7], s[2:3]
	s_mov_b64 s[10:11], s[2:3]
	s_mov_b64 s[0:1], s[2:3]
	v_readlane_b32 s14, v252, 37
	s_and_b64 vcc, exec, s[4:5]
	s_waitcnt lgkmcnt(0)
	s_barrier
	v_mbcnt_lo_u32_b32 v139, -1, 0
	v_mbcnt_hi_u32_b32 v139, -1, v139
	s_cbranch_vccnz .LBB0_568
	s_add_u32 s28, s6, 0xf800000
	s_addc_u32 s29, s7, 0
	s_add_u32 s4, s10, s8
	s_addc_u32 s5, s11, s9
	s_add_u32 s30, s4, 0x7800000
	s_addc_u32 s31, s5, 0
	s_add_u32 s10, s0, 0xb800000
	s_addc_u32 s11, s1, 0
	s_lshl_b32 s35, s14, 10
	v_lshlrev_b32_e32 v152, 4, v139
	v_add_u32_e32 v1, s35, v152
	v_add_u32_e32 v2, 0x2000, v1
	v_ashrrev_i32_e32 v3, 31, v2
	v_lshrrev_b32_e32 v3, 22, v3
	v_add_u32_e32 v3, v2, v3
	v_ashrrev_i32_e32 v145, 10, v3
	v_mul_i32_i24_e32 v3, 0x400, v145
	v_sub_u32_e32 v2, v2, v3
	v_lshrrev_b32_e32 v3, 4, v2
	v_bitop3_b32 v2, v3, v2, 32 bitop3:0x6c
	v_ashrrev_i32_e32 v3, 31, v2
	v_lshrrev_b32_e32 v3, 26, v3
	v_add_u32_e32 v3, v2, v3
	v_ashrrev_i32_e32 v150, 6, v3
	v_lshlrev_b32_e32 v4, 3, v145
	v_and_b32_e32 v3, 0xffc0, v3
	v_and_b32_e32 v4, -16, v4
	v_sub_u32_e32 v2, v2, v3
	v_add_u32_e32 v4, v150, v4
	v_lshrrev_b16_e32 v3, 7, v2
	v_and_b32_e32 v5, 3, v150
	s_mov_b32 s4, 0x3ffe0
	v_lshrrev_b32_e32 v6, 2, v4
	v_lshlrev_b32_e32 v7, 1, v4
	v_and_b32_e32 v3, 1, v3
	v_and_or_b32 v5, v4, s4, v5
	v_and_b32_e32 v6, 4, v6
	v_and_b32_e32 v7, 24, v7
	v_add_u16_e32 v2, v2, v3
	v_or3_b32 v5, v5, v6, v7
	v_lshlrev_b32_e32 v6, 5, v145
	v_ashrrev_i16_sdwa v2, v195, sext(v2) dst_sel:DWORD dst_unused:UNUSED_PAD src0_sel:DWORD src1_sel:BYTE_0
	v_and_b32_e32 v6, 32, v6
	v_bfe_i32 v151, v2, 0, 16
	v_add_lshl_u32 v2, v6, v151, 1
	v_lshl_add_u32 v130, v5, 14, v2
	v_lshl_add_u32 v132, v4, 14, v2
	v_ashrrev_i32_e32 v2, 31, v1
	v_lshrrev_b32_e32 v2, 22, v2
	v_add_u32_e32 v2, v1, v2
	v_ashrrev_i32_e32 v153, 10, v2
	v_mul_i32_i24_e32 v2, 0x400, v153
	v_sub_u32_e32 v1, v1, v2
	v_lshrrev_b32_e32 v2, 4, v1
	v_bitop3_b32 v1, v2, v1, 32 bitop3:0x6c
	v_ashrrev_i32_e32 v2, 31, v1
	v_lshrrev_b32_e32 v2, 26, v2
	v_add_u32_e32 v2, v1, v2
	v_lshlrev_b32_e32 v3, 3, v153
	v_ashrrev_i32_e32 v166, 6, v2
	v_and_b32_e32 v3, -16, v3
	v_add_u32_e32 v3, v166, v3
	v_and_b32_e32 v4, 3, v166
	v_lshrrev_b32_e32 v5, 2, v3
	v_lshlrev_b32_e32 v6, 1, v3
	v_and_b32_e32 v2, 0xc0, v2
	v_and_or_b32 v4, v3, s4, v4
	v_and_b32_e32 v5, 4, v5
	v_and_b32_e32 v6, 24, v6
	v_sub_u32_e32 v1, v1, v2
	s_ashr_i32 s1, s14, 2
	v_or3_b32 v4, v4, v5, v6
	v_lshlrev_b32_e32 v5, 5, v153
	v_ashrrev_i16_sdwa v1, v195, sext(v1) dst_sel:DWORD dst_unused:UNUSED_PAD src0_sel:DWORD src1_sel:BYTE_0
	s_lshl_b32 s0, s1, 6
	v_and_b32_e32 v5, 32, v5
	v_bfe_i32 v167, v1, 0, 16
	v_readlane_b32 s4, v251, 3
	v_and_b32_e32 v144, 15, v139
	v_add_lshl_u32 v1, v5, v167, 1
	s_add_i32 s4, s4, s0
	s_and_b32 s34, s14, 3
	v_lshl_add_u32 v134, v4, 14, v1
	v_lshl_add_u32 v136, v3, 14, v1
	v_or_b32_e32 v1, s4, v144
	v_and_b32_e32 v138, -16, v139
	v_lshlrev_b32_e32 v1, 12, v1
	v_lshl_add_u32 v168, s34, 6, v138
	v_readlane_b32 s4, v251, 5
	v_mov_b32_e32 v135, v0
	v_mov_b32_e32 v131, v0
	v_add3_u32 v1, s4, v168, v1
	v_mbcnt_lo_u32_b32 v66, -1, 0
	v_mbcnt_hi_u32_b32 v66, -1, v66
	v_lshrrev_b32_e32 v67, 2, v66
	v_and_b32_e32 v68, 15, v66
	v_sub_u32_e32 v67, v67, v68
	v_lshlrev_b32_e32 v67, 12, v67
	v_and_b32_e32 v68, 3, v66
	v_lshrrev_b32_e32 v66, 4, v66
	v_sub_u32_e32 v68, v68, v66
	v_lshl_add_u32 v67, v68, 4, v67
	v_add_u32_e32 v1, v1, v67
	v_add_u32_e32 v2, 0x10000, v1
	global_load_dwordx4 v[62:65], v1, s[10:11]
	global_load_dwordx4 v[58:61], v1, s[10:11] offset:256
	global_load_dwordx4 v[54:57], v2, s[10:11]
	global_load_dwordx4 v[50:53], v2, s[10:11] offset:256
	v_add_u32_e32 v2, 0x20000, v1
	global_load_dwordx4 v[46:49], v2, s[10:11]
	global_load_dwordx4 v[42:45], v2, s[10:11] offset:256
	v_add_u32_e32 v2, 0x30000, v1
	v_readlane_b32 s4, v251, 11
	global_load_dwordx4 v[38:41], v2, s[10:11]
	global_load_dwordx4 v[34:37], v2, s[10:11] offset:256
	v_add_u32_e32 v2, 0x80000, v1
	v_readlane_b32 s5, v251, 12
	s_add_u32 s8, s30, s4
	global_load_dwordx4 v[14:17], v2, s[10:11]
	global_load_dwordx4 v[10:13], v2, s[10:11] offset:256
	v_add_u32_e32 v2, 0x90000, v1
	s_addc_u32 s9, s31, s5
	s_add_i32 s36, s35, 0
	global_load_dwordx4 v[6:9], v2, s[10:11]
	global_load_dwordx4 v[26:29], v2, s[10:11] offset:256
	v_add_u32_e32 v2, 0xa0000, v1
	v_add_u32_e32 v1, 0xb0000, v1
	s_add_i32 m0, s36, 0x10000
	global_load_dwordx4 v[22:25], v2, s[10:11]
	global_load_dwordx4 v[18:21], v2, s[10:11] offset:256
	s_nop 0
	global_load_dwordx4 v[2:5], v1, s[10:11]
	global_load_dwordx4 v[30:33], v1, s[10:11] offset:256
	v_mov_b32_e32 v137, v0
	global_load_lds_dwordx4 v134, s[8:9]
	s_add_i32 m0, s36, 0x12000
	s_add_u32 s4, s8, 0x200000
	global_load_lds_dwordx4 v130, s[8:9]
	s_addc_u32 s5, s9, 0
	s_add_i32 m0, s36, 0x14000
	v_mov_b32_e32 v133, v0
	global_load_lds_dwordx4 v134, s[4:5]
	s_add_i32 m0, s36, 0x16000
	v_lshl_add_u64 v[148:149], s[8:9], 0, v[134:135]
	global_load_lds_dwordx4 v130, s[4:5]
	v_readlane_b32 s4, v251, 33
	v_readlane_b32 s5, v251, 34
	s_add_u32 s26, s28, s4
	s_addc_u32 s27, s29, s5
	s_add_i32 s37, s36, 0x2000
	s_mov_b32 m0, s36
	s_add_u32 s4, s26, 0x200000
	global_load_lds_dwordx4 v136, s[26:27]
	s_mov_b32 m0, s37
	s_addc_u32 s5, s27, 0
	s_add_i32 s38, s36, 0x4000
	global_load_lds_dwordx4 v132, s[26:27]
	s_mov_b32 m0, s38
	s_add_i32 s39, s36, 0x6000
	global_load_lds_dwordx4 v136, s[4:5]
	s_mov_b32 m0, s39
	s_cmp_eq_u32 s1, 1
	global_load_lds_dwordx4 v132, s[4:5]
	v_lshl_add_u64 v[146:147], s[8:9], 0, v[130:131]
	v_lshl_add_u64 v[140:141], s[26:27], 0, v[136:137]
	s_cselect_b64 s[12:13], -1, 0
	s_cmp_lg_u32 s1, 1
	v_lshl_add_u64 v[142:143], s[26:27], 0, v[132:133]
	s_cbranch_scc1 .LBB0_535
	s_barrier
; #define PG8_STAGE(bufoff, gbase, voff) do { _Pragma("unroll") for (int _i = 0; _i < 2; ++_i) \
;         __builtin_amdgcn_global_load_lds((const unsigned*)((const char*)(gbase) + (voff)[_i]), (PG8_LAS unsigned*)(lds + (bufoff) + ldsw + _i * 8192), 16, 0, 0); } while (0)
; #define PG8_WAIT_V(n) asm volatile("s_waitcnt vmcnt(" #n ")" ::: "memory")
; #define PG8_BAR __builtin_amdgcn_s_barrier()
;     __device__ __forceinline__ void init(f32x4 (&acc)[2][2][4][2], const Unit& u, int wr, int wc, int fr, int fq) const {
;     ...
;                 for (int bj = 0; bj < 2; ++bj) { const u32x4 w = *(const u32x4*)(bb + o + bj * HALF * 2);
;                     acc[ai][bj][m][0] = (f32x4){blo(w.x), bhi(w.x), blo(w.y), bhi(w.y)}; acc[ai][bj][m][1] = (f32x4){blo(w.z), bhi(w.z), blo(w.w), bhi(w.w)}; } }
; template <class Epi, class Sched, bool ALIGN_EPI = false, bool SP2 = false>
; __device__ __forceinline__ void gemm_phase(PG8_LAS unsigned char* lds, const Gemm g, const Sched& S, const Epi& E, const int wid_in) {
;     ...
;         PG8_WAIT_V(2); PG8_BAR;
;         PG8_STAGE(PG8_SB(1, 0), cB + kstep, voffB); PG8_STAGE(PG8_SA(1, 0), cA + kstep, voffA); PG8_STAGE(PG8_SB(1, 1), cB + hstep + kstep, voffB);
;         PG8_WAIT_V(6); PG8_BAR;
.LBB0_535:
	s_add_u32 s40, s2, 0x1fe00000
	s_waitcnt vmcnt(0)
	ds_bpermute_b32 v2, v254, v2
	ds_bpermute_b32 v3, v254, v3
	ds_bpermute_b32 v4, v254, v4
	ds_bpermute_b32 v5, v254, v5
	ds_bpermute_b32 v6, v254, v6
	ds_bpermute_b32 v7, v254, v7
	ds_bpermute_b32 v8, v254, v8
	ds_bpermute_b32 v9, v254, v9
	ds_bpermute_b32 v10, v254, v10
	ds_bpermute_b32 v11, v254, v11
	ds_bpermute_b32 v12, v254, v12
	ds_bpermute_b32 v13, v254, v13
	ds_bpermute_b32 v14, v254, v14
	ds_bpermute_b32 v15, v254, v15
	ds_bpermute_b32 v16, v254, v16
	ds_bpermute_b32 v17, v254, v17
	ds_bpermute_b32 v18, v254, v18
	ds_bpermute_b32 v19, v254, v19
	ds_bpermute_b32 v20, v254, v20
	ds_bpermute_b32 v21, v254, v21
	ds_bpermute_b32 v22, v254, v22
	ds_bpermute_b32 v23, v254, v23
	ds_bpermute_b32 v24, v254, v24
	ds_bpermute_b32 v25, v254, v25
	ds_bpermute_b32 v26, v254, v26
	ds_bpermute_b32 v27, v254, v27
	ds_bpermute_b32 v28, v254, v28
	ds_bpermute_b32 v29, v254, v29
	ds_bpermute_b32 v30, v254, v30
	ds_bpermute_b32 v31, v254, v31
	ds_bpermute_b32 v32, v254, v32
	ds_bpermute_b32 v33, v254, v33
	ds_bpermute_b32 v34, v254, v34
	ds_bpermute_b32 v35, v254, v35
	ds_bpermute_b32 v36, v254, v36
	ds_bpermute_b32 v37, v254, v37
	ds_bpermute_b32 v38, v254, v38
	ds_bpermute_b32 v39, v254, v39
	ds_bpermute_b32 v40, v254, v40
	ds_bpermute_b32 v41, v254, v41
	ds_bpermute_b32 v42, v254, v42
	ds_bpermute_b32 v43, v254, v43
	ds_bpermute_b32 v44, v254, v44
	ds_bpermute_b32 v45, v254, v45
	ds_bpermute_b32 v46, v254, v46
	ds_bpermute_b32 v47, v254, v47
	ds_bpermute_b32 v48, v254, v48
	ds_bpermute_b32 v49, v254, v49
	ds_bpermute_b32 v50, v254, v50
	ds_bpermute_b32 v51, v254, v51
	ds_bpermute_b32 v52, v254, v52
	ds_bpermute_b32 v53, v254, v53
	ds_bpermute_b32 v54, v254, v54
	ds_bpermute_b32 v55, v254, v55
	ds_bpermute_b32 v56, v254, v56
	ds_bpermute_b32 v57, v254, v57
	ds_bpermute_b32 v58, v254, v58
	ds_bpermute_b32 v59, v254, v59
	ds_bpermute_b32 v60, v254, v60
	ds_bpermute_b32 v61, v254, v61
	ds_bpermute_b32 v62, v254, v62
	ds_bpermute_b32 v63, v254, v63
	ds_bpermute_b32 v64, v254, v64
	ds_bpermute_b32 v65, v254, v65
	s_waitcnt lgkmcnt(0)
	v_lshlrev_b32_e32 v86, 16, v42
	v_and_b32_e32 v87, 0xffff0000, v42
	v_lshlrev_b32_e32 v88, 16, v43
	v_and_b32_e32 v89, 0xffff0000, v43
	s_addc_u32 s41, s3, 0
	s_add_i32 m0, s36, 0x18000
	v_lshl_add_u64 v[42:43], v[148:149], 0, s[98:99]
	s_waitcnt vmcnt(2)
	s_barrier
; #define PG8_STAGE(bufoff, gbase, voff) do { _Pragma("unroll") for (int _i = 0; _i < 2; ++_i) \
;         __builtin_amdgcn_global_load_lds((const unsigned*)((const char*)(gbase) + (voff)[_i]), (PG8_LAS unsigned*)(lds + (bufoff) + ldsw + _i * 8192), 16, 0, 0); } while (0)
; #define PG8_WAIT_V(n) asm volatile("s_waitcnt vmcnt(" #n ")" ::: "memory")
; #define PG8_BAR __builtin_amdgcn_s_barrier()
;     __device__ __forceinline__ void init(f32x4 (&acc)[2][2][4][2], const Unit& u, int wr, int wc, int fr, int fq) const {
;     ...
;                 for (int bj = 0; bj < 2; ++bj) { const u32x4 w = *(const u32x4*)(bb + o + bj * HALF * 2);
;                     acc[ai][bj][m][0] = (f32x4){blo(w.x), bhi(w.x), blo(w.y), bhi(w.y)}; acc[ai][bj][m][1] = (f32x4){blo(w.z), bhi(w.z), blo(w.w), bhi(w.w)}; } }
; template <class Epi, class Sched, bool ALIGN_EPI = false, bool SP2 = false>
; __device__ __forceinline__ void gemm_phase(PG8_LAS unsigned char* lds, const Gemm g, const Sched& S, const Epi& E, const int wid_in) {
;     ...
;     const int aoff = lds_byte(wr * 64 + fr, fq * 8), boff = lds_byte(wc * 32 + fr, fq * 8);
;     ...
;         PG8_WAIT_V(2); PG8_BAR;
;         PG8_STAGE(PG8_SB(1, 0), cB + kstep, voffB); PG8_STAGE(PG8_SA(1, 0), cA + kstep, voffA); PG8_STAGE(PG8_SB(1, 1), cB + hstep + kstep, voffB);
;         PG8_WAIT_V(6); PG8_BAR;
	global_load_lds_dwordx4 v[42:43], off
	v_lshl_add_u64 v[42:43], v[146:147], 0, s[98:99]
	s_add_i32 m0, s36, 0x1a000
	s_add_i32 s42, s36, 0x8000
	s_add_i32 s43, s36, 0xa000
	global_load_lds_dwordx4 v[42:43], off
	v_lshl_add_u64 v[42:43], v[140:141], 0, s[98:99]
	s_mov_b32 m0, s42
	s_add_u32 s2, s8, 0x200080
	global_load_lds_dwordx4 v[42:43], off
	v_lshl_add_u64 v[42:43], v[142:143], 0, s[98:99]
	s_mov_b32 m0, s43
	s_addc_u32 s3, s9, 0
	global_load_lds_dwordx4 v[42:43], off
	s_add_i32 m0, s36, 0x1c000
	v_lshl_add_u64 v[42:43], s[2:3], 0, v[134:135]
	global_load_lds_dwordx4 v[42:43], off
	v_lshl_add_u64 v[42:43], s[2:3], 0, v[130:131]
	s_add_i32 m0, s36, 0x1e000
	v_or_b32_e32 v146, s0, v144
	global_load_lds_dwordx4 v[42:43], off
	v_ashrrev_i32_e32 v1, 4, v139
	v_lshlrev_b32_e32 v140, 6, v146
	v_and_b32_e32 v139, 48, v139
	s_movk_i32 s2, 0x3c0
	v_and_b32_e32 v141, 0xfffffc00, v152
	v_lshlrev_b32_e32 v143, 2, v146
	v_and_or_b32 v140, v140, s2, v139
	v_lshl_add_u32 v142, s1, 13, v141
	v_and_b32_e32 v143, 32, v143
	v_bitop3_b32 v152, v140, v142, v143 bitop3:0xde
	v_lshl_add_u32 v140, s34, 12, v141
	v_lshlrev_b32_e32 v141, 2, v144
	v_lshl_or_b32 v139, v144, 6, v139
	v_and_b32_e32 v141, 32, v141
	v_bitop3_b32 v147, v139, v140, v141 bitop3:0xde
	s_cmp_lt_u32 s14, 4
	v_lshlrev_b32_e32 v140, 17, v153
	v_lshlrev_b32_e32 v142, 17, v145
	s_cselect_b64 s[14:15], -1, 0
	s_lshl_b32 s1, s34, 7
	v_and_b32_e32 v140, 0xfffc0000, v140
	v_and_b32_e32 v142, 0xfffc0000, v142
	s_waitcnt vmcnt(6)
	v_lshl_add_u32 v148, v1, 5, s1
	s_ashr_i32 s1, s0, 31
	v_lshl_add_u32 v140, v166, 14, v140
	v_and_b32_e32 v141, 1, v153
	v_lshl_add_u32 v142, v150, 14, v142
	v_and_b32_e32 v143, 1, v145
	v_lshl_or_b32 v140, v141, 6, v140
	v_lshl_or_b32 v142, v143, 6, v142
	s_lshl_b64 s[16:17], s[0:1], 2
	v_readlane_b32 s0, v251, 31
	v_lshlrev_b32_e32 v118, 16, v62
	v_and_b32_e32 v119, 0xffff0000, v62
	v_lshlrev_b32_e32 v120, 16, v63
	v_and_b32_e32 v121, 0xffff0000, v63
	v_lshlrev_b32_e32 v114, 16, v64
	v_and_b32_e32 v115, 0xffff0000, v64
	v_lshlrev_b32_e32 v116, 16, v65
	v_and_b32_e32 v117, 0xffff0000, v65
	v_lshlrev_b32_e32 v122, 16, v58
	v_and_b32_e32 v123, 0xffff0000, v58
	v_lshlrev_b32_e32 v124, 16, v59
	v_and_b32_e32 v125, 0xffff0000, v59
	v_lshlrev_b32_e32 v126, 16, v60
	v_and_b32_e32 v127, 0xffff0000, v60
	v_lshlrev_b32_e32 v128, 16, v61
	v_and_b32_e32 v129, 0xffff0000, v61
	v_lshlrev_b32_e32 v98, 16, v54
	v_and_b32_e32 v99, 0xffff0000, v54
	v_lshlrev_b32_e32 v100, 16, v55
	v_and_b32_e32 v101, 0xffff0000, v55
	v_lshlrev_b32_e32 v106, 16, v56
	v_and_b32_e32 v107, 0xffff0000, v56
	v_lshlrev_b32_e32 v108, 16, v57
	v_and_b32_e32 v109, 0xffff0000, v57
	v_lshlrev_b32_e32 v102, 16, v50
	v_and_b32_e32 v103, 0xffff0000, v50
	v_lshlrev_b32_e32 v104, 16, v51
	v_and_b32_e32 v105, 0xffff0000, v51
	v_lshlrev_b32_e32 v110, 16, v52
	v_and_b32_e32 v111, 0xffff0000, v52
	v_lshlrev_b32_e32 v112, 16, v53
	v_and_b32_e32 v113, 0xffff0000, v53
	v_lshlrev_b32_e32 v82, 16, v46
	v_and_b32_e32 v83, 0xffff0000, v46
	v_lshlrev_b32_e32 v84, 16, v47
	v_and_b32_e32 v85, 0xffff0000, v47
	v_lshlrev_b32_e32 v90, 16, v48
	v_and_b32_e32 v91, 0xffff0000, v48
	v_lshlrev_b32_e32 v92, 16, v49
	v_and_b32_e32 v93, 0xffff0000, v49
	v_lshlrev_b32_e32 v94, 16, v44
	v_and_b32_e32 v95, 0xffff0000, v44
	v_lshlrev_b32_e32 v96, 16, v45
	v_and_b32_e32 v97, 0xffff0000, v45
	v_lshlrev_b32_e32 v74, 16, v38
	v_and_b32_e32 v75, 0xffff0000, v38
	v_lshlrev_b32_e32 v76, 16, v39
	v_and_b32_e32 v77, 0xffff0000, v39
	v_lshlrev_b32_e32 v66, 16, v40
	v_and_b32_e32 v67, 0xffff0000, v40
	v_lshlrev_b32_e32 v68, 16, v41
	v_and_b32_e32 v69, 0xffff0000, v41
	v_lshlrev_b32_e32 v70, 16, v34
	v_and_b32_e32 v71, 0xffff0000, v34
	v_lshlrev_b32_e32 v72, 16, v35
	v_and_b32_e32 v73, 0xffff0000, v35
	v_lshlrev_b32_e32 v78, 16, v36
	v_and_b32_e32 v79, 0xffff0000, v36
	v_lshlrev_b32_e32 v80, 16, v37
	v_and_b32_e32 v81, 0xffff0000, v37
	v_lshlrev_b32_e32 v34, 16, v14
	v_and_b32_e32 v35, 0xffff0000, v14
	v_lshlrev_b32_e32 v36, 16, v15
	v_and_b32_e32 v37, 0xffff0000, v15
	v_lshlrev_b32_e32 v46, 16, v16
	v_and_b32_e32 v47, 0xffff0000, v16
	v_lshlrev_b32_e32 v48, 16, v17
	v_and_b32_e32 v49, 0xffff0000, v17
	v_lshlrev_b32_e32 v38, 16, v10
	v_and_b32_e32 v39, 0xffff0000, v10
	v_lshlrev_b32_e32 v40, 16, v11
	v_and_b32_e32 v41, 0xffff0000, v11
	v_lshlrev_b32_e32 v54, 16, v12
	v_and_b32_e32 v55, 0xffff0000, v12
	v_lshlrev_b32_e32 v56, 16, v13
	v_and_b32_e32 v57, 0xffff0000, v13
	v_lshlrev_b32_e32 v10, 16, v6
	v_and_b32_e32 v11, 0xffff0000, v6
	v_lshlrev_b32_e32 v12, 16, v7
	v_and_b32_e32 v13, 0xffff0000, v7
	v_lshlrev_b32_e32 v6, 16, v8
	v_and_b32_e32 v7, 0xffff0000, v8
	v_lshlrev_b32_e32 v8, 16, v9
	v_and_b32_e32 v9, 0xffff0000, v9
	v_lshlrev_b32_e32 v14, 16, v26
	v_and_b32_e32 v15, 0xffff0000, v26
	v_lshlrev_b32_e32 v16, 16, v27
	v_and_b32_e32 v17, 0xffff0000, v27
	v_lshlrev_b32_e32 v26, 16, v28
	v_and_b32_e32 v27, 0xffff0000, v28
	v_lshlrev_b32_e32 v28, 16, v29
	v_and_b32_e32 v29, 0xffff0000, v29
	v_lshlrev_b32_e32 v42, 16, v22
	v_and_b32_e32 v43, 0xffff0000, v22
	v_lshlrev_b32_e32 v44, 16, v23
	v_and_b32_e32 v45, 0xffff0000, v23
	v_lshlrev_b32_e32 v58, 16, v24
	v_and_b32_e32 v59, 0xffff0000, v24
	v_lshlrev_b32_e32 v60, 16, v25
	v_and_b32_e32 v61, 0xffff0000, v25
	v_lshlrev_b32_e32 v50, 16, v18
	v_and_b32_e32 v51, 0xffff0000, v18
	v_lshlrev_b32_e32 v52, 16, v19
	v_and_b32_e32 v53, 0xffff0000, v19
	v_lshlrev_b32_e32 v62, 16, v20
	v_and_b32_e32 v63, 0xffff0000, v20
	v_lshlrev_b32_e32 v64, 16, v21
	v_and_b32_e32 v65, 0xffff0000, v21
	v_lshlrev_b32_e32 v22, 16, v2
	v_and_b32_e32 v23, 0xffff0000, v2
	v_lshlrev_b32_e32 v24, 16, v3
	v_and_b32_e32 v25, 0xffff0000, v3
	v_lshlrev_b32_e32 v2, 16, v4
	v_and_b32_e32 v3, 0xffff0000, v4
	v_lshlrev_b32_e32 v4, 16, v5
	v_and_b32_e32 v5, 0xffff0000, v5
	v_lshlrev_b32_e32 v18, 16, v30
	v_and_b32_e32 v19, 0xffff0000, v30
	v_lshlrev_b32_e32 v20, 16, v31
	v_and_b32_e32 v21, 0xffff0000, v31
	v_lshlrev_b32_e32 v30, 16, v32
	v_and_b32_e32 v31, 0xffff0000, v32
	v_lshlrev_b32_e32 v32, 16, v33
	v_and_b32_e32 v33, 0xffff0000, v33
	v_cmp_eq_u32_e64 s[4:5], 2, v1
	v_ashrrev_i32_e32 v139, 31, v138
	v_lshl_add_u32 v149, v146, 12, v168
	v_lshl_add_u32 v140, v167, 1, v140
	v_mov_b32_e32 v141, v0
	v_lshl_add_u32 v142, v151, 1, v142
	v_mov_b32_e32 v143, v0
	s_mov_b32 s44, 0
	v_add_u32_e32 v150, 0, v152
	v_lshlrev_b32_e32 v144, 2, v144
	v_readlane_b32 s33, v251, 4
	s_mov_b32 s45, s0
	s_barrier
	v_readlane_b32 s1, v251, 32
	s_branch .LBB0_538

; #define PG8_BAR __builtin_amdgcn_s_barrier()
;     __device__ __forceinline__ void init(f32x4 (&acc)[2][2][4][2], const Unit& u, int wr, int wc, int fr, int fq) const {
;         const int row0 = u.pm * BM + wr * 64 + fr; const int col0 = u.pn * BM + wc * 32 + 8 * fq;
;         const unsigned ob0 = ((unsigned)row0 * LDC + (unsigned)col0) * 2u; const char* bb = (const char*)xb;
; #pragma unroll
;         for (int ai = 0; ai < 2; ++ai)
; #pragma unroll
;             for (int m = 0; m < 4; ++m) { const unsigned o = ob0 + (unsigned)((ai * HALF + m * 16) * LDC * 2);
; #pragma unroll
;                 for (int bj = 0; bj < 2; ++bj) { const u32x4 w = *(const u32x4*)(bb + o + bj * HALF * 2);
;                     acc[ai][bj][m][0] = (f32x4){blo(w.x), bhi(w.x), blo(w.y), bhi(w.y)}; acc[ai][bj][m][1] = (f32x4){blo(w.z), bhi(w.z), blo(w.w), bhi(w.w)}; } }
; template <class Epi, class Sched, bool ALIGN_EPI = false, bool SP2 = false>
; __device__ __forceinline__ void gemm_phase(PG8_LAS unsigned char* lds, const Gemm g, const Sched& S, const Epi& E, const int wid_in) {
;     ...
;         if constexpr (!Epi::AFTER_DRAIN) { E(acc, cur, wr, wc, fr, fq); S.done(cur); }
;         if (!has_next) break;
;         E.init(acc, nxt, wr, wc, fr, fq);
;         cur = nxt; cA = nA; cB = nB; ++ui;
;         if constexpr (ALIGN_EPI) { if (wr == 1) PG8_BAR; }
.LBB0_564:
	s_or_b64 exec, exec, s[2:3]
	s_andn2_b64 vcc, exec, s[6:7]
	s_mov_b64 s[0:1], -1
	global_store_dword v[66:67], v2, off offset:512
	s_cbranch_vccnz .LBB0_537
	s_lshl_b32 s0, s18, 9
	s_lshl_b32 s1, s20, 20
	s_add_i32 s1, s1, s0
	v_add_u32_e32 v2, s1, v149
	v_mbcnt_lo_u32_b32 v66, -1, 0
	v_mbcnt_hi_u32_b32 v66, -1, v66
	v_lshrrev_b32_e32 v67, 2, v66
	v_and_b32_e32 v68, 15, v66
	v_sub_u32_e32 v67, v67, v68
	v_lshlrev_b32_e32 v67, 12, v67
	v_and_b32_e32 v68, 3, v66
	v_lshrrev_b32_e32 v66, 4, v66
	v_sub_u32_e32 v68, v68, v66
	v_lshl_add_u32 v67, v68, 4, v67
	v_add_u32_e32 v2, v2, v67
	v_add_u32_e32 v3, 0x10000, v2
	global_load_dwordx4 v[62:65], v2, s[10:11]
	global_load_dwordx4 v[58:61], v2, s[10:11] offset:256
	global_load_dwordx4 v[54:57], v3, s[10:11]
	global_load_dwordx4 v[50:53], v3, s[10:11] offset:256
	v_add_u32_e32 v3, 0x20000, v2
	global_load_dwordx4 v[46:49], v3, s[10:11]
	global_load_dwordx4 v[42:45], v3, s[10:11] offset:256
	v_add_u32_e32 v3, 0x30000, v2
	global_load_dwordx4 v[38:41], v3, s[10:11]
	global_load_dwordx4 v[34:37], v3, s[10:11] offset:256
	v_add_u32_e32 v3, 0x80000, v2
	global_load_dwordx4 v[14:17], v3, s[10:11]
	global_load_dwordx4 v[10:13], v3, s[10:11] offset:256
	v_add_u32_e32 v3, 0x90000, v2
	global_load_dwordx4 v[6:9], v3, s[10:11]
	global_load_dwordx4 v[26:29], v3, s[10:11] offset:256
	v_add_u32_e32 v3, 0xa0000, v2
	v_add_u32_e32 v30, 0xb0000, v2
	global_load_dwordx4 v[22:25], v3, s[10:11]
	global_load_dwordx4 v[18:21], v3, s[10:11] offset:256
	s_waitcnt lgkmcnt(0)
	global_load_dwordx4 v[2:5], v30, s[10:11]
	s_nop 0
	global_load_dwordx4 v[30:33], v30, s[10:11] offset:256
	s_andn2_b64 vcc, exec, s[12:13]
	s_cbranch_vccnz .LBB0_536
	s_barrier
	s_branch .LBB0_536
